# P5 work split: scan workgroups take the last 2 of 28 layer-1 weight-copy items per wave after their scans
# baseline (speedup 1.0000x reference)
; #define LAS __attribute__((address_space(3)))
; __global__ void __launch_bounds__(NTHREADS, 2) fwd(Args a) {
;     ...
;         const int nsb = G >= 256 ? 128 : G;
;         if (bx < nsb) for (int sid = bx; sid < 128; sid += nsb) scan_chunked(a, lds, sid, tid);
;         const int tb = G >= 256 ? bx - 128 : bx, ntb = G >= 256 ? G - 128 : G;
;         if (tb >= 0) {
;             LAS float* scr = (LAS float*)(lds + wave * 16384);
;             float x[32], xn[32];
;             for (int u = tb; u < ATT_P5; u += ntb) attn_unit(a, lds, u, tid, lane, wave);
;             static_assert(L1_P5 <= TR_I2, "the phase-5 items are all gm_w_in items");
;             const int jst = ntb * NWAVES; int j = tb * NWAVES + wave;
;             auto ldi = [&](int jj, float (&xx)[32]) { tr_load_nc(a.in[I_GWIN], 3 * CW, 2, jj < L1_P5 ? jj : L1_P5 - 1, lane, TR_NB2, xx); };
;             auto sti = [&](int jj, const float (&xx)[32]) { tr_store((bf16*)(a.ws + WS_WGIN), D, scr, jj, lane, TR_NB2, xx); };
;             float xc[32];
;             ldi(j, x); ldi(j + jst, xn);
;             while (j + 2 * jst < L1_P5) {
.LBB0_637:
	s_add_i32 s4, s2, 0xffffff80
	s_and_b64 s[0:1], s[74:75], exec
	s_cselect_b32 s18, s4, s2
	s_movk_i32 s99, 0x7000
	s_movk_i32 s100, 0x6fff
	s_cbranch_scc0 .Lp5_cls
	s_cmp_lt_i32 s18, 0
	s_cbranch_scc1 .Lp5_scancls
	s_movk_i32 s99, 0x6800
	s_movk_i32 s100, 0x67ff
	s_branch .Lp5_cls
.Lp5_scancls:
	s_add_i32 s18, s2, 0xd00
.Lp5_cls:
	s_ashr_i32 s17, s26, 6
	s_add_i32 s4, s28, 0xffffff80
	s_and_b64 s[0:1], s[74:75], exec
	s_cselect_b32 s16, s4, s28
	s_cmpk_gt_i32 s18, 0x3ff
	s_cbranch_scc1 .LBB0_664
	s_lshl_b32 s0, s17, 5
	s_and_b32 s4, s0, 0x60
	s_waitcnt vmcnt(0)
	v_ashrrev_i32_e32 v7, 2, v147
	s_movk_i32 s0, 0x4200
	v_mov_b64_e32 v[4:5], s[62:63]
	v_mad_i64_i32 v[152:153], s[0:1], v7, s0, v[4:5]
	v_ashrrev_i32_e32 v155, 3, v147
	s_movk_i32 s0, 0x140
	v_lshlrev_b32_e32 v6, 3, v147
	v_mul_lo_u32 v168, v155, s0
	s_movk_i32 s0, 0xc0
	v_and_b32_e32 v3, 15, v147
	v_mov_b32_e32 v149, 0
	v_and_b32_e32 v148, 48, v1
	v_and_b32_e32 v2, 56, v6
	v_and_b32_e32 v4, 24, v6
	v_lshlrev_b32_e32 v6, 4, v147
	v_mul_lo_u32 v170, v7, s0
	v_lshrrev_b32_e32 v8, 2, v1
	v_or_b32_e32 v146, s4, v3
	v_lshl_add_u64 v[150:151], s[50:51], 0, v[148:149]
	v_add_u32_e32 v5, 0, v168
	v_and_b32_e32 v169, 0x70, v6
	v_add_u32_e32 v7, 0, v170
	v_and_b32_e32 v171, 48, v6
	v_and_b32_e32 v6, 48, v147
	v_and_b32_e32 v154, 12, v8
	v_lshlrev_b32_e32 v148, 1, v2
	v_mbcnt_lo_u32_b32 v2, -1, 0
	s_ashr_i32 s19, s26, 8
	s_mov_b32 s7, 0
	s_sub_i32 s20, s4, 63
	s_or_b32 s21, s4, 0x11f
	v_mul_u32_u24_e32 v172, 0x140, v3
	v_or_b32_e32 v173, 0x100, v146
	v_add_u32_e32 v174, -1, v146
	v_or_b32_e32 v175, 16, v146
	v_or_b32_e32 v176, 0x110, v146
	v_add_u32_e32 v177, 15, v146
	v_mul_u32_u24_e32 v178, 0xc0, v3
	v_add_u32_e32 v179, 0, v6
	s_movk_i32 s22, 0x6c00
	v_mov_b32_e32 v180, 0x6c00
	v_mov_b64_e32 v[156:157], s[50:51]
	s_mov_b64 s[8:9], 0x1000
	s_movk_i32 s23, 0x1000
	v_mov_b32_e32 v181, 0x210000
	v_lshlrev_b32_e32 v158, 1, v4
	v_mov_b32_e32 v159, v149
	v_add_u32_e32 v182, v5, v169
	v_add_u32_e32 v183, v7, v171
	s_mov_b32 s24, 0xff800000
	v_mbcnt_hi_u32_b32 v184, -1, v2
	v_lshlrev_b32_e32 v160, 1, v154
	v_mov_b32_e32 v185, 0xff800000
	s_mov_b32 s25, s18
	s_branch .LBB0_641

; __device__ __forceinline__ int src_col(int mat, int c) {
;     ...
;     if (mat == 2) {
;         if (c < CW) return CW + c;
;         const int cc = c - CW, tile = cc >> 8, w = cc & 255;
;         return w < 128 ? (tile * 128 + w) : (2 * CW + tile * 128 + (w - 128));
;     }
; __device__ __forceinline__ void tr_load_nc(const float* W, int N, int mat, int item, int lane, int nblk, float (&x)[32]) {
;     const int kb = item / nblk, nb = item % nblk, k0 = 64 * kb, n0 = 32 * nb;
;     const int sc = src_col(mat, n0 + (lane & 31));
;     const float* wp = W + (size_t)(k0 + (lane >> 5)) * N + sc;
; #pragma unroll
;     for (int i = 0; i < 32; ++i) x[i] = wp[(size_t)(2 * i) * N];
; }
; __global__ void __launch_bounds__(NTHREADS, 2) fwd(Args a) {
;     ...
;             auto ldi = [&](int jj, float (&xx)[32]) { tr_load_nc(a.in[I_GWIN], 3 * CW, 2, jj < L1_P5 ? jj : L1_P5 - 1, lane, TR_NB2, xx); };
;     ...
;             ldi(j, x); ldi(j + jst, xn);
.LBB0_664:
	s_lshl_b32 s0, s18, 3
	s_add_i32 s10, s17, s0
	s_min_i32 s0, s10, s100
	s_mul_hi_i32 s1, s0, 0x38e38e39
	s_lshr_b32 s4, s1, 31
	s_ashr_i32 s6, s1, 8
	s_add_i32 s6, s6, s4
	s_mul_i32 s1, s6, 0x480
	s_sub_i32 s0, s0, s1
	s_lshl_b32 s4, s0, 5
	s_waitcnt vmcnt(0)
	v_and_b32_e32 v6, 31, v147
	v_or_b32_e32 v3, s4, v6
	s_movk_i32 s0, 0x2fff
	v_cmp_lt_i32_e32 vcc, s0, v3
	s_and_saveexec_b64 s[0:1], vcc
	s_xor_b64 s[0:1], exec, s[0:1]
	s_cbranch_execz .LBB0_670
	s_add_i32 s7, s4, 0xffffd000
	s_movk_i32 s4, 0x7f
	s_lshr_b32 s7, s7, 1
	v_cmp_gt_u32_sdwa s[4:5], v3, s4 src0_sel:BYTE_0 src1_sel:DWORD
	s_and_b32 s7, s7, 0x7fffff80
	s_and_saveexec_b64 s[8:9], s[4:5]
	s_xor_b64 s[4:5], exec, s[8:9]
	v_add_u32_sdwa v2, v3, s7 dst_sel:DWORD dst_unused:UNUSED_PAD src0_sel:BYTE_0 src1_sel:DWORD
	v_add_u32_e32 v2, 0x5f80, v2
	s_andn2_saveexec_b64 s[4:5], s[4:5]
	v_or_b32_sdwa v2, s7, v3 dst_sel:DWORD dst_unused:UNUSED_PAD src0_sel:DWORD src1_sel:BYTE_0
	s_or_b64 exec, exec, s[4:5]
.LBB0_670:
	s_andn2_saveexec_b64 s[0:1], s[0:1]
	v_add_u32_e32 v2, 0x3000, v3
	s_or_b64 exec, exec, s[0:1]
	v_readlane_b32 s76, v254, 2
	v_lshrrev_b32_e32 v7, 5, v1
	v_readlane_b32 s84, v254, 10
	v_readlane_b32 s85, v254, 11
	v_lshl_or_b32 v3, s6, 6, v7
	s_mov_b32 s0, 0x24000
	v_mov_b64_e32 v[4:5], s[84:85]
	v_mad_i64_i32 v[4:5], s[0:1], v3, s0, v[4:5]
	v_ashrrev_i32_e32 v3, 31, v2
	v_lshl_add_u64 v[2:3], v[2:3], 2, v[4:5]
	v_add_co_u32_e32 v4, vcc, 0x48000, v2
	s_lshl_b32 s8, s16, 3
	s_nop 0
	v_addc_co_u32_e32 v5, vcc, 0, v3, vcc
	v_add_co_u32_e32 v12, vcc, 0x90000, v2
	s_add_i32 s6, s10, s8
	s_nop 0
	v_addc_co_u32_e32 v13, vcc, 0, v3, vcc
	v_add_co_u32_e32 v14, vcc, 0xd8000, v2
	s_min_i32 s0, s6, s100
	s_nop 0
	v_addc_co_u32_e32 v15, vcc, 0, v3, vcc
	v_add_co_u32_e32 v16, vcc, 0x120000, v2
	s_mul_hi_i32 s1, s0, 0x38e38e39
	s_nop 0
	v_addc_co_u32_e32 v17, vcc, 0, v3, vcc
	v_add_co_u32_e32 v18, vcc, 0x168000, v2
	s_lshr_b32 s4, s1, 31
	s_nop 0
	v_addc_co_u32_e32 v19, vcc, 0, v3, vcc
	v_add_co_u32_e32 v20, vcc, 0x1b0000, v2
	s_ashr_i32 s7, s1, 8
	s_nop 0
	v_addc_co_u32_e32 v21, vcc, 0, v3, vcc
	v_add_co_u32_e32 v22, vcc, 0x1f8000, v2
	s_add_i32 s7, s7, s4
	s_nop 0
	v_addc_co_u32_e32 v23, vcc, 0, v3, vcc
	global_load_dword v8, v[2:3], off
	global_load_dword v11, v[4:5], off
	global_load_dword v10, v[12:13], off
	s_nop 0
	global_load_dword v14, v[14:15], off
	s_nop 0
	global_load_dword v9, v[16:17], off
	global_load_dword v13, v[18:19], off
	global_load_dword v12, v[20:21], off
	global_load_dword v15, v[22:23], off
	v_add_co_u32_e32 v4, vcc, 0x240000, v2
	s_mul_i32 s1, s7, 0x480
	s_nop 0
	v_addc_co_u32_e32 v5, vcc, 0, v3, vcc
	v_add_co_u32_e32 v18, vcc, 0x288000, v2
	s_sub_i32 s0, s0, s1
	s_nop 0
	v_addc_co_u32_e32 v19, vcc, 0, v3, vcc
	v_add_co_u32_e32 v20, vcc, 0x2d0000, v2
	s_lshl_b32 s4, s0, 5
	s_nop 0
	v_addc_co_u32_e32 v21, vcc, 0, v3, vcc
	v_add_co_u32_e32 v22, vcc, 0x318000, v2
	s_movk_i32 s0, 0x2fff
	s_nop 0
	v_addc_co_u32_e32 v23, vcc, 0, v3, vcc
	v_add_co_u32_e32 v24, vcc, 0x360000, v2
	v_readlane_b32 s77, v254, 3
	s_nop 0
	v_addc_co_u32_e32 v25, vcc, 0, v3, vcc
	v_add_co_u32_e32 v26, vcc, 0x3a8000, v2
	v_readlane_b32 s78, v254, 4
	s_nop 0
	v_addc_co_u32_e32 v27, vcc, 0, v3, vcc
	v_add_co_u32_e32 v28, vcc, 0x3f0000, v2
	v_readlane_b32 s79, v254, 5
	s_nop 0
	v_addc_co_u32_e32 v29, vcc, 0, v3, vcc
	v_add_co_u32_e32 v30, vcc, 0x438000, v2
	v_readlane_b32 s80, v254, 6
	s_nop 0
	v_addc_co_u32_e32 v31, vcc, 0, v3, vcc
	global_load_dword v16, v[4:5], off
	s_nop 0
	global_load_dword v19, v[18:19], off
	s_nop 0
	global_load_dword v18, v[20:21], off
	s_nop 0
	global_load_dword v22, v[22:23], off
	s_nop 0
	global_load_dword v17, v[24:25], off
	global_load_dword v21, v[26:27], off
	global_load_dword v20, v[28:29], off
	global_load_dword v23, v[30:31], off
	v_add_co_u32_e32 v4, vcc, 0x480000, v2
	v_readlane_b32 s81, v254, 7
	s_nop 0
	v_addc_co_u32_e32 v5, vcc, 0, v3, vcc
	v_add_co_u32_e32 v24, vcc, 0x4c8000, v2
	v_readlane_b32 s82, v254, 8
	s_nop 0
	v_addc_co_u32_e32 v25, vcc, 0, v3, vcc
	v_add_co_u32_e32 v26, vcc, 0x510000, v2
	v_readlane_b32 s83, v254, 9
	s_nop 0
	v_addc_co_u32_e32 v27, vcc, 0, v3, vcc
	v_add_co_u32_e32 v28, vcc, 0x558000, v2
	v_readlane_b32 s86, v254, 12
	s_nop 0
	v_addc_co_u32_e32 v29, vcc, 0, v3, vcc
	v_add_co_u32_e32 v30, vcc, 0x5a0000, v2
	v_readlane_b32 s87, v254, 13
	s_nop 0
	v_addc_co_u32_e32 v31, vcc, 0, v3, vcc
	v_add_co_u32_e32 v36, vcc, 0x5e8000, v2
	v_readlane_b32 s88, v254, 14
	s_nop 0
	v_addc_co_u32_e32 v37, vcc, 0, v3, vcc
	v_add_co_u32_e32 v40, vcc, 0x630000, v2
	v_readlane_b32 s89, v254, 15
	s_nop 0
	v_addc_co_u32_e32 v41, vcc, 0, v3, vcc
	v_add_co_u32_e32 v42, vcc, 0x678000, v2
	v_readlane_b32 s90, v254, 16
	s_nop 0
	v_addc_co_u32_e32 v43, vcc, 0, v3, vcc
	global_load_dword v32, v[4:5], off
	global_load_dword v35, v[24:25], off
	global_load_dword v34, v[26:27], off
	global_load_dword v38, v[28:29], off
	global_load_dword v33, v[30:31], off
	s_nop 0
	global_load_dword v37, v[36:37], off
	s_nop 0
	global_load_dword v36, v[40:41], off
	global_load_dword v39, v[42:43], off
	v_add_co_u32_e32 v4, vcc, 0x6c0000, v2
	v_readlane_b32 s91, v254, 17
	s_nop 0
	v_addc_co_u32_e32 v5, vcc, 0, v3, vcc
	v_add_co_u32_e32 v24, vcc, 0x708000, v2
	s_nop 1
	v_addc_co_u32_e32 v25, vcc, 0, v3, vcc
	v_add_co_u32_e32 v26, vcc, 0x750000, v2
	s_nop 1
	v_addc_co_u32_e32 v27, vcc, 0, v3, vcc
	v_add_co_u32_e32 v28, vcc, 0x798000, v2
	s_nop 1
	v_addc_co_u32_e32 v29, vcc, 0, v3, vcc
	v_add_co_u32_e32 v30, vcc, 0x7e0000, v2
	s_nop 1
	v_addc_co_u32_e32 v31, vcc, 0, v3, vcc
	v_add_co_u32_e32 v40, vcc, 0x828000, v2
	s_nop 1
	v_addc_co_u32_e32 v41, vcc, 0, v3, vcc
	v_add_co_u32_e32 v42, vcc, 0x870000, v2
	s_nop 1
	v_addc_co_u32_e32 v43, vcc, 0, v3, vcc
	v_add_co_u32_e32 v2, vcc, 0x8b8000, v2
	s_nop 1
	v_addc_co_u32_e32 v3, vcc, 0, v3, vcc
	global_load_dword v48, v[4:5], off
	global_load_dword v51, v[24:25], off
	global_load_dword v50, v[26:27], off
	global_load_dword v54, v[28:29], off
	global_load_dword v49, v[30:31], off
	global_load_dword v53, v[40:41], off
	global_load_dword v52, v[42:43], off
	global_load_dword v55, v[2:3], off
	v_or_b32_e32 v3, s4, v6
	v_cmp_lt_i32_e32 vcc, s0, v3
	s_and_saveexec_b64 s[0:1], vcc
	s_xor_b64 s[0:1], exec, s[0:1]
	s_cbranch_execz .LBB0_678
	s_add_i32 s9, s4, 0xffffd000
	s_movk_i32 s4, 0x7f
	s_lshr_b32 s9, s9, 1
	v_cmp_gt_u32_sdwa s[4:5], v3, s4 src0_sel:BYTE_0 src1_sel:DWORD
	s_and_b32 s9, s9, 0x7fffff80
	s_and_saveexec_b64 s[12:13], s[4:5]
	s_xor_b64 s[4:5], exec, s[12:13]
	v_add_u32_sdwa v2, v3, s9 dst_sel:DWORD dst_unused:UNUSED_PAD src0_sel:BYTE_0 src1_sel:DWORD
	v_add_u32_e32 v2, 0x5f80, v2
	s_andn2_saveexec_b64 s[4:5], s[4:5]
	v_or_b32_sdwa v2, s9, v3 dst_sel:DWORD dst_unused:UNUSED_PAD src0_sel:DWORD src1_sel:BYTE_0
	s_or_b64 exec, exec, s[4:5]
; __device__ __forceinline__ void tr_load_nc(const float* W, int N, int mat, int item, int lane, int nblk, float (&x)[32]) {
;     const int kb = item / nblk, nb = item % nblk, k0 = 64 * kb, n0 = 32 * nb;
;     const int sc = src_col(mat, n0 + (lane & 31));
;     const float* wp = W + (size_t)(k0 + (lane >> 5)) * N + sc;
; #pragma unroll
;     for (int i = 0; i < 32; ++i) x[i] = wp[(size_t)(2 * i) * N];
; }
; __global__ void __launch_bounds__(NTHREADS, 2) fwd(Args a) {
;     ...
;             ldi(j, x); ldi(j + jst, xn);
;             while (j + 2 * jst < L1_P5) {
.LBB0_678:
	s_andn2_saveexec_b64 s[0:1], s[0:1]
	v_add_u32_e32 v2, 0x3000, v3
	s_or_b64 exec, exec, s[0:1]
	v_readlane_b32 s76, v254, 2
	v_readlane_b32 s84, v254, 10
	v_readlane_b32 s85, v254, 11
	v_lshl_or_b32 v3, s7, 6, v7
	s_mov_b32 s11, 0x24000
	v_mov_b64_e32 v[4:5], s[84:85]
	v_mad_i64_i32 v[4:5], s[0:1], v3, s11, v[4:5]
	v_ashrrev_i32_e32 v3, 31, v2
	v_lshl_add_u64 v[2:3], v[2:3], 2, v[4:5]
	v_add_co_u32_e32 v4, vcc, 0x48000, v2
	s_lshl_b32 s0, s17, 14
	s_nop 0
	v_addc_co_u32_e32 v5, vcc, 0, v3, vcc
	v_add_co_u32_e32 v28, vcc, 0x90000, v2
	s_add_i32 s9, s0, 0
	s_nop 0
	v_addc_co_u32_e32 v29, vcc, 0, v3, vcc
	v_add_co_u32_e32 v30, vcc, 0xd8000, v2
	s_add_i32 s0, s6, s8
	s_nop 0
	v_addc_co_u32_e32 v31, vcc, 0, v3, vcc
	v_add_co_u32_e32 v40, vcc, 0x120000, v2
	s_cmp_gt_i32 s0, s100
	s_nop 0
	v_addc_co_u32_e32 v41, vcc, 0, v3, vcc
	v_add_co_u32_e32 v42, vcc, 0x168000, v2
	v_readlane_b32 s77, v254, 3
	s_nop 0
	v_addc_co_u32_e32 v43, vcc, 0, v3, vcc
	v_add_co_u32_e32 v44, vcc, 0x1b0000, v2
	v_readlane_b32 s78, v254, 4
	s_nop 0
	v_addc_co_u32_e32 v45, vcc, 0, v3, vcc
	v_add_co_u32_e32 v46, vcc, 0x1f8000, v2
	v_readlane_b32 s79, v254, 5
	s_nop 0
	v_addc_co_u32_e32 v47, vcc, 0, v3, vcc
	global_load_dword v24, v[2:3], off
	global_load_dword v26, v[4:5], off
	global_load_dword v25, v[28:29], off
	s_nop 0
	global_load_dword v28, v[30:31], off
	global_load_dword v27, v[40:41], off
	s_nop 0
	global_load_dword v30, v[42:43], off
	global_load_dword v29, v[44:45], off
	global_load_dword v31, v[46:47], off
	v_add_co_u32_e32 v4, vcc, 0x240000, v2
	v_readlane_b32 s80, v254, 6
	s_nop 0
	v_addc_co_u32_e32 v5, vcc, 0, v3, vcc
	v_add_co_u32_e32 v42, vcc, 0x288000, v2
	v_readlane_b32 s81, v254, 7
	s_nop 0
	v_addc_co_u32_e32 v43, vcc, 0, v3, vcc
	v_add_co_u32_e32 v44, vcc, 0x2d0000, v2
	v_readlane_b32 s82, v254, 8
	s_nop 0
	v_addc_co_u32_e32 v45, vcc, 0, v3, vcc
	v_add_co_u32_e32 v46, vcc, 0x318000, v2
	v_readlane_b32 s83, v254, 9
	s_nop 0
	v_addc_co_u32_e32 v47, vcc, 0, v3, vcc
	v_add_co_u32_e32 v56, vcc, 0x360000, v2
	v_readlane_b32 s86, v254, 12
	s_nop 0
	v_addc_co_u32_e32 v57, vcc, 0, v3, vcc
	v_add_co_u32_e32 v58, vcc, 0x3a8000, v2
	v_readlane_b32 s87, v254, 13
	s_nop 0
	v_addc_co_u32_e32 v59, vcc, 0, v3, vcc
	v_add_co_u32_e32 v60, vcc, 0x3f0000, v2
	v_readlane_b32 s88, v254, 14
	s_nop 0
	v_addc_co_u32_e32 v61, vcc, 0, v3, vcc
	v_add_co_u32_e32 v62, vcc, 0x438000, v2
	v_readlane_b32 s89, v254, 15
	s_nop 0
	v_addc_co_u32_e32 v63, vcc, 0, v3, vcc
	global_load_dword v40, v[4:5], off
	s_nop 0
	global_load_dword v42, v[42:43], off
	s_nop 0
	global_load_dword v41, v[44:45], off
	s_nop 0
	global_load_dword v44, v[46:47], off
	global_load_dword v43, v[56:57], off
	s_nop 0
	global_load_dword v46, v[58:59], off
	global_load_dword v45, v[60:61], off
	global_load_dword v47, v[62:63], off
	v_add_co_u32_e32 v4, vcc, 0x480000, v2
	v_readlane_b32 s90, v254, 16
	s_nop 0
	v_addc_co_u32_e32 v5, vcc, 0, v3, vcc
	v_add_co_u32_e32 v58, vcc, 0x4c8000, v2
	v_readlane_b32 s91, v254, 17
	s_nop 0
	v_addc_co_u32_e32 v59, vcc, 0, v3, vcc
	v_add_co_u32_e32 v60, vcc, 0x510000, v2
	s_nop 1
	v_addc_co_u32_e32 v61, vcc, 0, v3, vcc
	v_add_co_u32_e32 v62, vcc, 0x558000, v2
	s_nop 1
	v_addc_co_u32_e32 v63, vcc, 0, v3, vcc
	v_add_co_u32_e32 v64, vcc, 0x5a0000, v2
	s_nop 1
	v_addc_co_u32_e32 v65, vcc, 0, v3, vcc
	v_add_co_u32_e32 v66, vcc, 0x5e8000, v2
	s_nop 1
	v_addc_co_u32_e32 v67, vcc, 0, v3, vcc
	v_add_co_u32_e32 v68, vcc, 0x630000, v2
	s_nop 1
	v_addc_co_u32_e32 v69, vcc, 0, v3, vcc
	v_add_co_u32_e32 v70, vcc, 0x678000, v2
	s_nop 1
	v_addc_co_u32_e32 v71, vcc, 0, v3, vcc
	global_load_dword v56, v[4:5], off
	s_nop 0
	global_load_dword v58, v[58:59], off
	s_nop 0
	global_load_dword v57, v[60:61], off
	s_nop 0
	global_load_dword v60, v[62:63], off
	global_load_dword v59, v[64:65], off
	s_nop 0
	global_load_dword v62, v[66:67], off
	global_load_dword v61, v[68:69], off
	global_load_dword v63, v[70:71], off
	v_add_co_u32_e32 v4, vcc, 0x6c0000, v2
	s_nop 1
	v_addc_co_u32_e32 v5, vcc, 0, v3, vcc
	v_add_co_u32_e32 v66, vcc, 0x708000, v2
	s_nop 1
	v_addc_co_u32_e32 v67, vcc, 0, v3, vcc
	v_add_co_u32_e32 v68, vcc, 0x750000, v2
	s_nop 1
	v_addc_co_u32_e32 v69, vcc, 0, v3, vcc
	v_add_co_u32_e32 v70, vcc, 0x798000, v2
	s_nop 1
	v_addc_co_u32_e32 v71, vcc, 0, v3, vcc
	v_add_co_u32_e32 v72, vcc, 0x7e0000, v2
	s_nop 1
	v_addc_co_u32_e32 v73, vcc, 0, v3, vcc
	v_add_co_u32_e32 v74, vcc, 0x828000, v2
	s_nop 1
	v_addc_co_u32_e32 v75, vcc, 0, v3, vcc
	v_add_co_u32_e32 v76, vcc, 0x870000, v2
	s_nop 1
	v_addc_co_u32_e32 v77, vcc, 0, v3, vcc
	v_add_co_u32_e32 v2, vcc, 0x8b8000, v2
	s_nop 1
	v_addc_co_u32_e32 v3, vcc, 0, v3, vcc
	global_load_dword v64, v[4:5], off
	s_nop 0
	global_load_dword v67, v[66:67], off
	s_nop 0
	global_load_dword v66, v[68:69], off
	s_nop 0
	global_load_dword v70, v[70:71], off
	s_nop 0
	global_load_dword v69, v[72:73], off
	s_nop 0
	global_load_dword v72, v[74:75], off
	global_load_dword v71, v[76:77], off
	global_load_dword v73, v[2:3], off
	s_cbranch_scc1 .LBB0_707
	v_lshlrev_b32_e32 v2, 2, v6
	v_mul_u32_u24_e32 v3, 0x84, v7
	v_add3_u32 v65, s9, v2, v3
	v_lshlrev_b32_e32 v2, 3, v1
	v_lshrrev_b32_e32 v68, 3, v1
	v_and_b32_e32 v2, 56, v2
	s_lshl_b32 s12, s16, 4
	s_mul_i32 s13, s16, 24
	v_mul_u32_u24_e32 v4, 0x84, v2
	v_lshlrev_b32_e32 v2, 1, v2
	v_mov_b32_e32 v3, 0
	v_lshlrev_b32_e32 v5, 2, v68
	v_lshl_add_u64 v[2:3], s[92:93], 0, v[2:3]
	v_add3_u32 v74, s9, v4, v5
	v_or_b32_e32 v75, 8, v68
	v_or_b32_e32 v76, 16, v68
	v_or_b32_e32 v77, 24, v68
	v_lshl_or_b32 v78, s10, 5, v68
	s_lshl_b32 s14, s13, 5
	s_sub_i32 s15, s13, s12
	s_add_i32 s16, s13, s8
	s_movk_i32 s17, 0x2fff
	s_movk_i32 s18, 0x7f
	s_branch .LBB0_683
; __device__ __forceinline__ void tr_load_nc(const float* W, int N, int mat, int item, int lane, int nblk, float (&x)[32]) {
;     const int kb = item / nblk, nb = item % nblk, k0 = 64 * kb, n0 = 32 * nb;
;     const int sc = src_col(mat, n0 + (lane & 31));
;     const float* wp = W + (size_t)(k0 + (lane >> 5)) * N + sc;
; #pragma unroll
;     for (int i = 0; i < 32; ++i) x[i] = wp[(size_t)(2 * i) * N];
; }
; __global__ void __launch_bounds__(NTHREADS, 2) fwd(Args a) {
;     ...
;                 ldi(j + 2 * jst, xc); sti(j, x);
;                 ldi(j + 3 * jst, x);  sti(j + jst, xn);
;                 ldi(j + 4 * jst, xn); sti(j + 2 * jst, xc);
.LBB0_682:
	s_or_b64 exec, exec, s[4:5]
	v_readlane_b32 s76, v254, 2
	v_readlane_b32 s84, v254, 10
	v_readlane_b32 s85, v254, 11
	v_lshl_or_b32 v5, s1, 6, v7
	s_ashr_i32 s1, s0, 31
	v_mov_b64_e32 v[24:25], s[84:85]
	v_mad_i64_i32 v[24:25], s[4:5], v5, s11, v[24:25]
	v_ashrrev_i32_e32 v5, 31, v4
	v_lshl_add_u64 v[4:5], v[4:5], 2, v[24:25]
	v_add_co_u32_e32 v26, vcc, 0x48000, v4
	v_add_u32_e32 v78, s14, v78
	s_nop 0
	v_addc_co_u32_e32 v27, vcc, 0, v5, vcc
	v_add_co_u32_e32 v28, vcc, 0x90000, v4
	v_readlane_b32 s77, v254, 3
	s_nop 0
	v_addc_co_u32_e32 v29, vcc, 0, v5, vcc
	v_add_co_u32_e32 v30, vcc, 0xd8000, v4
	v_readlane_b32 s78, v254, 4
	s_nop 0
	v_addc_co_u32_e32 v31, vcc, 0, v5, vcc
	v_add_co_u32_e32 v40, vcc, 0x120000, v4
	v_readlane_b32 s79, v254, 5
	s_nop 0
	v_addc_co_u32_e32 v41, vcc, 0, v5, vcc
	v_add_co_u32_e32 v42, vcc, 0x168000, v4
	v_readlane_b32 s80, v254, 6
	s_nop 0
	v_addc_co_u32_e32 v43, vcc, 0, v5, vcc
	v_add_co_u32_e32 v44, vcc, 0x1b0000, v4
	v_readlane_b32 s81, v254, 7
	s_nop 0
	v_addc_co_u32_e32 v45, vcc, 0, v5, vcc
	v_add_co_u32_e32 v46, vcc, 0x1f8000, v4
	v_readlane_b32 s82, v254, 8
	s_nop 0
	v_addc_co_u32_e32 v47, vcc, 0, v5, vcc
	global_load_dword v24, v[4:5], off
	s_nop 0
	global_load_dword v26, v[26:27], off
	s_nop 0
	global_load_dword v25, v[28:29], off
	s_nop 0
	global_load_dword v28, v[30:31], off
	global_load_dword v27, v[40:41], off
	s_nop 0
	global_load_dword v30, v[42:43], off
	global_load_dword v29, v[44:45], off
	global_load_dword v31, v[46:47], off
	v_add_co_u32_e32 v40, vcc, 0x240000, v4
	v_readlane_b32 s83, v254, 9
	s_nop 0
	v_addc_co_u32_e32 v41, vcc, 0, v5, vcc
	v_add_co_u32_e32 v42, vcc, 0x288000, v4
	v_readlane_b32 s86, v254, 12
	s_nop 0
	v_addc_co_u32_e32 v43, vcc, 0, v5, vcc
	v_add_co_u32_e32 v44, vcc, 0x2d0000, v4
	v_readlane_b32 s87, v254, 13
	s_nop 0
	v_addc_co_u32_e32 v45, vcc, 0, v5, vcc
	v_add_co_u32_e32 v46, vcc, 0x318000, v4
	v_readlane_b32 s88, v254, 14
	s_nop 0
	v_addc_co_u32_e32 v47, vcc, 0, v5, vcc
	v_add_co_u32_e32 v56, vcc, 0x360000, v4
	v_readlane_b32 s89, v254, 15
	s_nop 0
	v_addc_co_u32_e32 v57, vcc, 0, v5, vcc
	v_add_co_u32_e32 v58, vcc, 0x3a8000, v4
	v_readlane_b32 s90, v254, 16
	s_nop 0
	v_addc_co_u32_e32 v59, vcc, 0, v5, vcc
	v_add_co_u32_e32 v60, vcc, 0x3f0000, v4
	v_readlane_b32 s91, v254, 17
	s_nop 0
	v_addc_co_u32_e32 v61, vcc, 0, v5, vcc
	v_add_co_u32_e32 v62, vcc, 0x438000, v4
	s_nop 1
	v_addc_co_u32_e32 v63, vcc, 0, v5, vcc
	global_load_dword v40, v[40:41], off
	s_nop 0
	global_load_dword v42, v[42:43], off
	s_nop 0
	global_load_dword v41, v[44:45], off
	s_nop 0
	global_load_dword v44, v[46:47], off
	global_load_dword v43, v[56:57], off
	s_nop 0
	global_load_dword v46, v[58:59], off
	global_load_dword v45, v[60:61], off
	global_load_dword v47, v[62:63], off
	v_add_co_u32_e32 v56, vcc, 0x480000, v4
	s_nop 1
	v_addc_co_u32_e32 v57, vcc, 0, v5, vcc
	v_add_co_u32_e32 v58, vcc, 0x4c8000, v4
	s_nop 1
	v_addc_co_u32_e32 v59, vcc, 0, v5, vcc
	v_add_co_u32_e32 v60, vcc, 0x510000, v4
	s_nop 1
	v_addc_co_u32_e32 v61, vcc, 0, v5, vcc
	v_add_co_u32_e32 v62, vcc, 0x558000, v4
	s_nop 1
	v_addc_co_u32_e32 v63, vcc, 0, v5, vcc
	v_add_co_u32_e32 v66, vcc, 0x5a0000, v4
	s_nop 1
	v_addc_co_u32_e32 v67, vcc, 0, v5, vcc
	v_add_co_u32_e32 v70, vcc, 0x5e8000, v4
	s_nop 1
	v_addc_co_u32_e32 v71, vcc, 0, v5, vcc
	v_add_co_u32_e32 v72, vcc, 0x630000, v4
	s_nop 1
	v_addc_co_u32_e32 v73, vcc, 0, v5, vcc
	v_add_co_u32_e32 v118, vcc, 0x678000, v4
	s_nop 1
	v_addc_co_u32_e32 v119, vcc, 0, v5, vcc
	global_load_dword v56, v[56:57], off
	s_nop 0
	global_load_dword v58, v[58:59], off
	s_nop 0
	global_load_dword v57, v[60:61], off
	s_nop 0
	global_load_dword v60, v[62:63], off
	global_load_dword v59, v[66:67], off
	s_nop 0
	global_load_dword v62, v[70:71], off
	global_load_dword v61, v[72:73], off
	global_load_dword v63, v[118:119], off
	v_add_co_u32_e32 v66, vcc, 0x6c0000, v4
	s_nop 1
	v_addc_co_u32_e32 v67, vcc, 0, v5, vcc
	v_add_co_u32_e32 v70, vcc, 0x708000, v4
	s_nop 1
	v_addc_co_u32_e32 v71, vcc, 0, v5, vcc
	v_add_co_u32_e32 v72, vcc, 0x750000, v4
	s_nop 1
	v_addc_co_u32_e32 v73, vcc, 0, v5, vcc
	v_add_co_u32_e32 v118, vcc, 0x798000, v4
	s_nop 1
	v_addc_co_u32_e32 v119, vcc, 0, v5, vcc
	v_add_co_u32_e32 v120, vcc, 0x7e0000, v4
	s_nop 1
	v_addc_co_u32_e32 v121, vcc, 0, v5, vcc
	v_add_co_u32_e32 v122, vcc, 0x828000, v4
	s_nop 1
	v_addc_co_u32_e32 v123, vcc, 0, v5, vcc
	v_add_co_u32_e32 v124, vcc, 0x870000, v4
	s_nop 1
	v_addc_co_u32_e32 v125, vcc, 0, v5, vcc
	v_add_co_u32_e32 v4, vcc, 0x8b8000, v4
	s_nop 1
	v_addc_co_u32_e32 v5, vcc, 0, v5, vcc
	global_load_dword v64, v[66:67], off
	s_nop 0
	global_load_dword v67, v[70:71], off
	global_load_dword v66, v[72:73], off
	s_nop 0
	global_load_dword v70, v[118:119], off
	global_load_dword v69, v[120:121], off
	global_load_dword v72, v[122:123], off
	global_load_dword v71, v[124:125], off
	global_load_dword v73, v[4:5], off
	s_waitcnt vmcnt(63)
; #define GAS __attribute__((address_space(1)))
; #define LAS __attribute__((address_space(3)))
; #define LDS_WAIT() asm volatile("s_waitcnt lgkmcnt(0)" ::: "memory")
; __device__ __forceinline__ unsigned pk2(float lo, float hi) { return pg8::cvt_pk_bf16(lo, hi); }
; __device__ __forceinline__ void tr_store(bf16* WT, int K, LAS float* scr, int item, int lane, int nblk, const float (&x)[32]) {
;     const int kb = item / nblk, nb = item % nblk, k0 = 64 * kb, n0 = 32 * nb;
; #pragma unroll
;     for (int i = 0; i < 32; ++i) { const int kk = 2 * i + (lane >> 5); scr[kk * 33 + (lane & 31)] = x[i]; }
;     LDS_WAIT(); asm volatile("" ::: "memory");
;     const int c = lane & 7;
; #pragma unroll
;     for (int j = 0; j < 4; ++j) { const int n = (lane >> 3) + 8 * j; const LAS float* s = scr + (8 * c) * 33 + n;
;         v4u o; o.x = pk2(s[0 * 33], s[1 * 33]); o.y = pk2(s[2 * 33], s[3 * 33]); o.z = pk2(s[4 * 33], s[5 * 33]); o.w = pk2(s[6 * 33], s[7 * 33]);
;         *(GAS v4u*)(WT + (size_t)(n0 + n) * K + k0 + 8 * c) = o; }
;     LDS_WAIT(); asm volatile("" ::: "memory");
; __global__ void __launch_bounds__(NTHREADS, 2) fwd(Args a) {
;     ...
;             while (j + 2 * jst < L1_P5) {
	ds_write2_b32 v65, v79, v80 offset1:66
	ds_write2_b32 v65, v81, v82 offset0:132 offset1:198
	ds_write2_b32 v111, v83, v84 offset0:8 offset1:74
	ds_write2_b32 v111, v85, v86 offset0:140 offset1:206
	ds_write2_b32 v112, v87, v88 offset0:16 offset1:82
	ds_write2_b32 v112, v89, v90 offset0:148 offset1:214
	ds_write2_b32 v113, v91, v92 offset0:24 offset1:90
	ds_write2_b32 v113, v93, v94 offset0:156 offset1:222
	ds_write2_b32 v114, v95, v96 offset0:32 offset1:98
	ds_write2_b32 v114, v97, v98 offset0:164 offset1:230
	ds_write2_b32 v115, v99, v100 offset0:40 offset1:106
	ds_write2_b32 v115, v101, v102 offset0:172 offset1:238
	ds_write2_b32 v116, v103, v104 offset0:48 offset1:114
	ds_write2_b32 v116, v105, v106 offset0:180 offset1:246
	ds_write2_b32 v117, v107, v108 offset0:56 offset1:122
	ds_write2_b32 v117, v109, v110 offset0:188 offset1:254
	s_waitcnt lgkmcnt(0)
	ds_read2_b32 v[4:5], v74 offset1:33
	s_waitcnt lgkmcnt(0)
	v_cvt_pk_bf16_f32 v80, v4, v5
	ds_read2_b32 v[4:5], v74 offset0:66 offset1:99
	s_waitcnt lgkmcnt(0)
	v_cvt_pk_bf16_f32 v81, v4, v5
	ds_read2_b32 v[4:5], v74 offset0:132 offset1:165
	s_waitcnt lgkmcnt(0)
	v_cvt_pk_bf16_f32 v82, v4, v5
	ds_read2_b32 v[4:5], v74 offset0:198 offset1:231
	s_waitcnt lgkmcnt(0)
	v_cvt_pk_bf16_f32 v83, v4, v5
	v_or_b32_e32 v4, s19, v68
	v_ashrrev_i32_e32 v5, 31, v4
	v_lshl_add_u64 v[84:85], s[0:1], 1, v[2:3]
	v_lshlrev_b64 v[4:5], 13, v[4:5]
	v_lshl_add_u64 v[4:5], v[84:85], 0, v[4:5]
	ds_read2_b32 v[86:87], v74 offset0:8 offset1:41
	global_store_dwordx4 v[4:5], v[80:83], off
	s_add_i32 s0, s10, s12
	s_cmp_lt_i32 s0, s99
	s_waitcnt lgkmcnt(0)
	v_cvt_pk_bf16_f32 v80, v86, v87
	ds_read2_b32 v[4:5], v74 offset0:74 offset1:107
	s_waitcnt lgkmcnt(0)
	v_cvt_pk_bf16_f32 v81, v4, v5
	ds_read2_b32 v[4:5], v74 offset0:140 offset1:173
	s_waitcnt lgkmcnt(0)
	v_cvt_pk_bf16_f32 v82, v4, v5
	ds_read2_b32 v[4:5], v74 offset0:206 offset1:239
	s_waitcnt lgkmcnt(0)
	v_cvt_pk_bf16_f32 v83, v4, v5
	v_or_b32_e32 v4, s19, v75
	v_ashrrev_i32_e32 v5, 31, v4
	v_lshlrev_b64 v[4:5], 13, v[4:5]
	v_lshl_add_u64 v[4:5], v[84:85], 0, v[4:5]
	ds_read2_b32 v[86:87], v74 offset0:16 offset1:49
	global_store_dwordx4 v[4:5], v[80:83], off
	s_waitcnt lgkmcnt(0)
	s_nop 0
	v_cvt_pk_bf16_f32 v80, v86, v87
	ds_read2_b32 v[4:5], v74 offset0:82 offset1:115
	s_waitcnt lgkmcnt(0)
	v_cvt_pk_bf16_f32 v81, v4, v5
	ds_read2_b32 v[4:5], v74 offset0:148 offset1:181
	s_waitcnt lgkmcnt(0)
	v_cvt_pk_bf16_f32 v82, v4, v5
	ds_read2_b32 v[4:5], v74 offset0:214 offset1:247
	s_waitcnt lgkmcnt(0)
	v_cvt_pk_bf16_f32 v83, v4, v5
	v_or_b32_e32 v4, s19, v76
	v_ashrrev_i32_e32 v5, 31, v4
	v_lshlrev_b64 v[4:5], 13, v[4:5]
	v_lshl_add_u64 v[4:5], v[84:85], 0, v[4:5]
	ds_read2_b32 v[86:87], v74 offset0:24 offset1:57
	global_store_dwordx4 v[4:5], v[80:83], off
	s_waitcnt lgkmcnt(0)
	s_nop 0
	v_cvt_pk_bf16_f32 v80, v86, v87
	ds_read2_b32 v[4:5], v74 offset0:90 offset1:123
	s_waitcnt lgkmcnt(0)
	v_cvt_pk_bf16_f32 v81, v4, v5
	ds_read2_b32 v[4:5], v74 offset0:156 offset1:189
	s_waitcnt lgkmcnt(0)
	v_cvt_pk_bf16_f32 v82, v4, v5
	ds_read2_b32 v[4:5], v74 offset0:222 offset1:255
	s_waitcnt lgkmcnt(0)
	v_cvt_pk_bf16_f32 v83, v4, v5
	v_or_b32_e32 v4, s19, v77
	v_ashrrev_i32_e32 v5, 31, v4
	v_lshlrev_b64 v[4:5], 13, v[4:5]
	v_lshl_add_u64 v[4:5], v[84:85], 0, v[4:5]
	global_store_dwordx4 v[4:5], v[80:83], off
	s_waitcnt lgkmcnt(0)
	s_cbranch_scc0 .LBB0_707

; __device__ __forceinline__ void tr_load_nc(const float* W, int N, int mat, int item, int lane, int nblk, float (&x)[32]) {
;     const int kb = item / nblk, nb = item % nblk, k0 = 64 * kb, n0 = 32 * nb;
;     const int sc = src_col(mat, n0 + (lane & 31));
;     const float* wp = W + (size_t)(k0 + (lane >> 5)) * N + sc;
; #pragma unroll
;     for (int i = 0; i < 32; ++i) x[i] = wp[(size_t)(2 * i) * N];
; }
; __global__ void __launch_bounds__(NTHREADS, 2) fwd(Args a) {
;     ...
;                 ldi(j + 2 * jst, xc); sti(j, x);
;                 ldi(j + 3 * jst, x);  sti(j + jst, xn);
.LBB0_689:
	s_andn2_saveexec_b64 s[0:1], s[0:1]
	v_add_u32_e32 v4, 0x3000, v5
	s_or_b64 exec, exec, s[0:1]
	v_readlane_b32 s76, v254, 2
	s_lshl_b32 s0, s6, 6
	v_readlane_b32 s84, v254, 10
	v_readlane_b32 s85, v254, 11
	v_or_b32_e32 v5, s0, v7
	s_mul_hi_i32 s1, s20, 0x38e38e39
	v_mov_b64_e32 v[80:81], s[84:85]
	v_mad_i64_i32 v[80:81], s[4:5], v5, s11, v[80:81]
	v_ashrrev_i32_e32 v5, 31, v4
	v_lshl_add_u64 v[4:5], v[4:5], 2, v[80:81]
	v_add_co_u32_e32 v80, vcc, 0x48000, v4
	s_lshr_b32 s4, s1, 31
	s_nop 0
	v_addc_co_u32_e32 v81, vcc, 0, v5, vcc
	v_add_co_u32_e32 v82, vcc, 0x90000, v4
	s_ashr_i32 s1, s1, 8
	s_nop 0
	v_addc_co_u32_e32 v83, vcc, 0, v5, vcc
	v_add_co_u32_e32 v84, vcc, 0xd8000, v4
	s_add_i32 s1, s1, s4
	s_nop 0
	v_addc_co_u32_e32 v85, vcc, 0, v5, vcc
	v_add_co_u32_e32 v86, vcc, 0x120000, v4
	s_lshl_b32 s4, s1, 6
	s_nop 0
	v_addc_co_u32_e32 v87, vcc, 0, v5, vcc
	v_add_co_u32_e32 v88, vcc, 0x168000, v4
	s_mul_i32 s1, s1, 0xffff7000
	s_nop 0
	v_addc_co_u32_e32 v89, vcc, 0, v5, vcc
	v_add_co_u32_e32 v90, vcc, 0x1b0000, v4
	s_ashr_i32 s5, s4, 31
	s_nop 0
	v_addc_co_u32_e32 v91, vcc, 0, v5, vcc
	v_add_co_u32_e32 v92, vcc, 0x1f8000, v4
	s_add_i32 s10, s20, s13
	s_nop 0
	v_addc_co_u32_e32 v93, vcc, 0, v5, vcc
	global_load_dword v79, v[4:5], off
	s_nop 0
	global_load_dword v80, v[80:81], off
	s_nop 0
	global_load_dword v81, v[82:83], off
	s_nop 0
	global_load_dword v82, v[84:85], off
	global_load_dword v83, v[86:87], off
	s_nop 0
	global_load_dword v84, v[88:89], off
	global_load_dword v85, v[90:91], off
	global_load_dword v86, v[92:93], off
	v_add_co_u32_e32 v88, vcc, 0x240000, v4
	v_readlane_b32 s77, v254, 3
	s_nop 0
	v_addc_co_u32_e32 v89, vcc, 0, v5, vcc
	v_add_co_u32_e32 v90, vcc, 0x288000, v4
	v_readlane_b32 s78, v254, 4
	s_nop 0
	v_addc_co_u32_e32 v91, vcc, 0, v5, vcc
	v_add_co_u32_e32 v92, vcc, 0x2d0000, v4
	v_readlane_b32 s79, v254, 5
	s_nop 0
	v_addc_co_u32_e32 v93, vcc, 0, v5, vcc
	v_add_co_u32_e32 v94, vcc, 0x318000, v4
	v_readlane_b32 s80, v254, 6
	s_nop 0
	v_addc_co_u32_e32 v95, vcc, 0, v5, vcc
	v_add_co_u32_e32 v96, vcc, 0x360000, v4
	v_readlane_b32 s81, v254, 7
	s_nop 0
	v_addc_co_u32_e32 v97, vcc, 0, v5, vcc
	v_add_co_u32_e32 v98, vcc, 0x3a8000, v4
	v_readlane_b32 s82, v254, 8
	s_nop 0
	v_addc_co_u32_e32 v99, vcc, 0, v5, vcc
	v_add_co_u32_e32 v100, vcc, 0x3f0000, v4
	v_readlane_b32 s83, v254, 9
	s_nop 0
	v_addc_co_u32_e32 v101, vcc, 0, v5, vcc
	v_add_co_u32_e32 v102, vcc, 0x438000, v4
	v_readlane_b32 s86, v254, 12
	s_nop 0
	v_addc_co_u32_e32 v103, vcc, 0, v5, vcc
	global_load_dword v87, v[88:89], off
	s_nop 0
	global_load_dword v88, v[90:91], off
	global_load_dword v89, v[92:93], off
	s_nop 0
	global_load_dword v90, v[94:95], off
	global_load_dword v91, v[96:97], off
	global_load_dword v92, v[98:99], off
	global_load_dword v93, v[100:101], off
	s_nop 0
	global_load_dword v94, v[102:103], off
	v_add_co_u32_e32 v96, vcc, 0x480000, v4
	v_readlane_b32 s87, v254, 13
	s_nop 0
	v_addc_co_u32_e32 v97, vcc, 0, v5, vcc
	v_add_co_u32_e32 v98, vcc, 0x4c8000, v4
	v_readlane_b32 s88, v254, 14
	s_nop 0
	v_addc_co_u32_e32 v99, vcc, 0, v5, vcc
	v_add_co_u32_e32 v100, vcc, 0x510000, v4
	v_readlane_b32 s89, v254, 15
	s_nop 0
	v_addc_co_u32_e32 v101, vcc, 0, v5, vcc
	v_add_co_u32_e32 v102, vcc, 0x558000, v4
	v_readlane_b32 s90, v254, 16
	s_nop 0
	v_addc_co_u32_e32 v103, vcc, 0, v5, vcc
	v_add_co_u32_e32 v104, vcc, 0x5a0000, v4
	v_readlane_b32 s91, v254, 17
	s_nop 0
	v_addc_co_u32_e32 v105, vcc, 0, v5, vcc
	v_add_co_u32_e32 v106, vcc, 0x5e8000, v4
	s_nop 1
	v_addc_co_u32_e32 v107, vcc, 0, v5, vcc
	v_add_co_u32_e32 v108, vcc, 0x630000, v4
	s_nop 1
	v_addc_co_u32_e32 v109, vcc, 0, v5, vcc
	v_add_co_u32_e32 v110, vcc, 0x678000, v4
	s_nop 1
	v_addc_co_u32_e32 v111, vcc, 0, v5, vcc
	global_load_dword v95, v[96:97], off
	s_nop 0
	global_load_dword v96, v[98:99], off
	global_load_dword v97, v[100:101], off
	s_nop 0
	global_load_dword v98, v[102:103], off
	global_load_dword v99, v[104:105], off
	global_load_dword v100, v[106:107], off
	global_load_dword v101, v[108:109], off
	s_nop 0
	global_load_dword v102, v[110:111], off
	v_add_co_u32_e32 v104, vcc, 0x6c0000, v4
	s_nop 1
	v_addc_co_u32_e32 v105, vcc, 0, v5, vcc
	v_add_co_u32_e32 v106, vcc, 0x708000, v4
	s_nop 1
	v_addc_co_u32_e32 v107, vcc, 0, v5, vcc
	v_add_co_u32_e32 v108, vcc, 0x750000, v4
	s_nop 1
	v_addc_co_u32_e32 v109, vcc, 0, v5, vcc
	v_add_co_u32_e32 v110, vcc, 0x798000, v4
	s_nop 1
	v_addc_co_u32_e32 v111, vcc, 0, v5, vcc
	v_add_co_u32_e32 v112, vcc, 0x7e0000, v4
	s_nop 1
	v_addc_co_u32_e32 v113, vcc, 0, v5, vcc
	v_add_co_u32_e32 v114, vcc, 0x828000, v4
	s_nop 1
	v_addc_co_u32_e32 v115, vcc, 0, v5, vcc
	v_add_co_u32_e32 v116, vcc, 0x870000, v4
	s_nop 1
	v_addc_co_u32_e32 v117, vcc, 0, v5, vcc
	v_add_co_u32_e32 v4, vcc, 0x8b8000, v4
	s_nop 1
	v_addc_co_u32_e32 v5, vcc, 0, v5, vcc
	global_load_dword v103, v[104:105], off
	s_nop 0
	global_load_dword v104, v[106:107], off
	global_load_dword v105, v[108:109], off
	s_nop 0
	global_load_dword v106, v[110:111], off
	global_load_dword v107, v[112:113], off
	global_load_dword v108, v[114:115], off
	global_load_dword v109, v[116:117], off
	s_nop 0
	global_load_dword v110, v[4:5], off
	v_add_u32_e32 v111, 0x400, v65
	v_add_u32_e32 v112, 0x800, v65
	v_add_u32_e32 v113, 0xc00, v65
	v_add_u32_e32 v114, 0x1000, v65
	v_add_u32_e32 v115, 0x1400, v65
	v_add_u32_e32 v116, 0x1800, v65
	v_add_u32_e32 v117, 0x1c00, v65
	s_waitcnt vmcnt(63)
; #define GAS __attribute__((address_space(1)))
; #define LAS __attribute__((address_space(3)))
; #define LDS_WAIT() asm volatile("s_waitcnt lgkmcnt(0)" ::: "memory")
; __device__ __forceinline__ unsigned pk2(float lo, float hi) { return pg8::cvt_pk_bf16(lo, hi); }
; __device__ __forceinline__ void tr_store(bf16* WT, int K, LAS float* scr, int item, int lane, int nblk, const float (&x)[32]) {
;     const int kb = item / nblk, nb = item % nblk, k0 = 64 * kb, n0 = 32 * nb;
; #pragma unroll
;     for (int i = 0; i < 32; ++i) { const int kk = 2 * i + (lane >> 5); scr[kk * 33 + (lane & 31)] = x[i]; }
;     LDS_WAIT(); asm volatile("" ::: "memory");
;     const int c = lane & 7;
; #pragma unroll
;     for (int j = 0; j < 4; ++j) { const int n = (lane >> 3) + 8 * j; const LAS float* s = scr + (8 * c) * 33 + n;
;         v4u o; o.x = pk2(s[0 * 33], s[1 * 33]); o.y = pk2(s[2 * 33], s[3 * 33]); o.z = pk2(s[4 * 33], s[5 * 33]); o.w = pk2(s[6 * 33], s[7 * 33]);
;         *(GAS v4u*)(WT + (size_t)(n0 + n) * K + k0 + 8 * c) = o; }
;     LDS_WAIT(); asm volatile("" ::: "memory");
; __global__ void __launch_bounds__(NTHREADS, 2) fwd(Args a) {
;     ...
;                 ldi(j + 2 * jst, xc); sti(j, x);
;                 ldi(j + 3 * jst, x);  sti(j + jst, xn);
	ds_write2_b32 v65, v8, v11 offset1:66
	ds_write2_b32 v65, v10, v14 offset0:132 offset1:198
	ds_write2_b32 v111, v9, v13 offset0:8 offset1:74
	ds_write2_b32 v111, v12, v15 offset0:140 offset1:206
	ds_write2_b32 v112, v16, v19 offset0:16 offset1:82
	ds_write2_b32 v112, v18, v22 offset0:148 offset1:214
	ds_write2_b32 v113, v17, v21 offset0:24 offset1:90
	ds_write2_b32 v113, v20, v23 offset0:156 offset1:222
	ds_write2_b32 v114, v32, v35 offset0:32 offset1:98
	ds_write2_b32 v114, v34, v38 offset0:164 offset1:230
	ds_write2_b32 v115, v33, v37 offset0:40 offset1:106
	ds_write2_b32 v115, v36, v39 offset0:172 offset1:238
	ds_write2_b32 v116, v48, v51 offset0:48 offset1:114
	ds_write2_b32 v116, v50, v54 offset0:180 offset1:246
	ds_write2_b32 v117, v49, v53 offset0:56 offset1:122
	ds_write2_b32 v117, v52, v55 offset0:188 offset1:254
	s_waitcnt lgkmcnt(0)
	ds_read2_b32 v[4:5], v74 offset1:33
	s_waitcnt lgkmcnt(0)
	v_cvt_pk_bf16_f32 v8, v4, v5
	ds_read2_b32 v[4:5], v74 offset0:66 offset1:99
	s_waitcnt lgkmcnt(0)
	v_cvt_pk_bf16_f32 v9, v4, v5
	ds_read2_b32 v[4:5], v74 offset0:132 offset1:165
	s_waitcnt lgkmcnt(0)
	v_cvt_pk_bf16_f32 v10, v4, v5
	ds_read2_b32 v[4:5], v74 offset0:198 offset1:231
	s_waitcnt lgkmcnt(0)
	v_cvt_pk_bf16_f32 v11, v4, v5
	v_add_u32_e32 v4, s1, v78
	v_ashrrev_i32_e32 v5, 31, v4
	v_lshl_add_u64 v[12:13], s[4:5], 1, v[2:3]
	v_lshlrev_b64 v[16:17], 13, v[4:5]
	v_lshl_add_u64 v[16:17], v[12:13], 0, v[16:17]
	ds_read2_b32 v[14:15], v74 offset0:8 offset1:41
	global_store_dwordx4 v[16:17], v[8:11], off
	s_min_i32 s4, s10, s100
	s_mul_hi_i32 s1, s4, 0x38e38e39
	s_waitcnt lgkmcnt(0)
	v_cvt_pk_bf16_f32 v8, v14, v15
	ds_read2_b32 v[10:11], v74 offset0:74 offset1:107
	s_waitcnt lgkmcnt(0)
	v_cvt_pk_bf16_f32 v9, v10, v11
	ds_read2_b32 v[10:11], v74 offset0:140 offset1:173
	s_waitcnt lgkmcnt(0)
	v_cvt_pk_bf16_f32 v10, v10, v11
	ds_read2_b32 v[14:15], v74 offset0:206 offset1:239
	s_waitcnt lgkmcnt(0)
	v_cvt_pk_bf16_f32 v11, v14, v15
	v_add_u32_e32 v14, 8, v4
	v_ashrrev_i32_e32 v15, 31, v14
	v_lshlrev_b64 v[14:15], 13, v[14:15]
	v_lshl_add_u64 v[14:15], v[12:13], 0, v[14:15]
	ds_read2_b32 v[16:17], v74 offset0:16 offset1:49
	global_store_dwordx4 v[14:15], v[8:11], off
	s_lshr_b32 s5, s1, 31
	s_ashr_i32 s1, s1, 8
	s_waitcnt lgkmcnt(0)
	v_cvt_pk_bf16_f32 v8, v16, v17
	ds_read2_b32 v[10:11], v74 offset0:82 offset1:115
	s_waitcnt lgkmcnt(0)
	v_cvt_pk_bf16_f32 v9, v10, v11
	ds_read2_b32 v[10:11], v74 offset0:148 offset1:181
	s_waitcnt lgkmcnt(0)
	v_cvt_pk_bf16_f32 v10, v10, v11
	ds_read2_b32 v[14:15], v74 offset0:214 offset1:247
	s_waitcnt lgkmcnt(0)
	v_cvt_pk_bf16_f32 v11, v14, v15
	v_add_u32_e32 v14, 16, v4
	v_ashrrev_i32_e32 v15, 31, v14
	v_lshlrev_b64 v[14:15], 13, v[14:15]
	v_add_u32_e32 v4, 24, v4
	v_lshl_add_u64 v[14:15], v[12:13], 0, v[14:15]
	v_ashrrev_i32_e32 v5, 31, v4
	ds_read2_b32 v[16:17], v74 offset0:24 offset1:57
	global_store_dwordx4 v[14:15], v[8:11], off
	v_lshlrev_b64 v[4:5], 13, v[4:5]
	v_lshl_add_u64 v[4:5], v[12:13], 0, v[4:5]
	s_waitcnt lgkmcnt(0)
	v_cvt_pk_bf16_f32 v8, v16, v17
	ds_read2_b32 v[10:11], v74 offset0:90 offset1:123
	s_waitcnt lgkmcnt(0)
	v_cvt_pk_bf16_f32 v9, v10, v11
	ds_read2_b32 v[10:11], v74 offset0:156 offset1:189
	s_add_i32 s1, s1, s5
	s_waitcnt lgkmcnt(0)
	v_cvt_pk_bf16_f32 v10, v10, v11
	ds_read2_b32 v[14:15], v74 offset0:222 offset1:255
	s_waitcnt lgkmcnt(0)
	v_cvt_pk_bf16_f32 v11, v14, v15
	global_store_dwordx4 v[4:5], v[8:11], off
	s_mul_i32 s5, s1, 0x480
	s_waitcnt lgkmcnt(0)
	s_sub_i32 s4, s4, s5
	s_lshl_b32 s6, s4, 5
	v_or_b32_e32 v5, s6, v6
	v_cmp_lt_i32_e32 vcc, s17, v5
	s_and_saveexec_b64 s[4:5], vcc
	s_xor_b64 s[4:5], exec, s[4:5]
	s_cbranch_execz .LBB0_697
	s_add_i32 s21, s6, 0xffffd000
	s_lshr_b32 s21, s21, 1
	v_cmp_gt_u32_sdwa s[6:7], v5, s18 src0_sel:BYTE_0 src1_sel:DWORD
	s_and_b32 s21, s21, 0x7fffff80
	s_and_saveexec_b64 s[22:23], s[6:7]
	s_xor_b64 s[6:7], exec, s[22:23]
	v_add_u32_sdwa v4, v5, s21 dst_sel:DWORD dst_unused:UNUSED_PAD src0_sel:BYTE_0 src1_sel:DWORD
	v_add_u32_e32 v4, 0x5f80, v4
	s_andn2_saveexec_b64 s[6:7], s[6:7]
	v_or_b32_sdwa v4, s21, v5 dst_sel:DWORD dst_unused:UNUSED_PAD src0_sel:DWORD src1_sel:BYTE_0
	s_or_b64 exec, exec, s[6:7]
.LBB0_697:
	s_andn2_saveexec_b64 s[4:5], s[4:5]
	v_add_u32_e32 v4, 0x3000, v5
	s_or_b64 exec, exec, s[4:5]
	v_readlane_b32 s76, v254, 2
	v_readlane_b32 s84, v254, 10
	v_readlane_b32 s85, v254, 11
	v_lshl_or_b32 v5, s1, 6, v7
	s_add_i32 s1, s15, s20
	v_mov_b64_e32 v[8:9], s[84:85]
	v_mad_i64_i32 v[8:9], s[4:5], v5, s11, v[8:9]
	v_ashrrev_i32_e32 v5, 31, v4
	v_lshl_add_u64 v[4:5], v[4:5], 2, v[8:9]
	v_add_co_u32_e32 v10, vcc, 0x48000, v4
	s_mul_hi_i32 s4, s1, 0x38e38e39
	s_nop 0
	v_addc_co_u32_e32 v11, vcc, 0, v5, vcc
	v_add_co_u32_e32 v12, vcc, 0x90000, v4
	s_lshr_b32 s5, s4, 31
	s_nop 0
	v_addc_co_u32_e32 v13, vcc, 0, v5, vcc
	v_add_co_u32_e32 v14, vcc, 0xd8000, v4
	s_ashr_i32 s4, s4, 8
	s_nop 0
	v_addc_co_u32_e32 v15, vcc, 0, v5, vcc
	v_add_co_u32_e32 v16, vcc, 0x120000, v4
	s_add_i32 s5, s4, s5
	s_nop 0
	v_addc_co_u32_e32 v17, vcc, 0, v5, vcc
	v_add_co_u32_e32 v18, vcc, 0x168000, v4
	s_lshl_b32 s4, s5, 6
	s_nop 0
	v_addc_co_u32_e32 v19, vcc, 0, v5, vcc
	v_add_co_u32_e32 v20, vcc, 0x1b0000, v4
	s_mulk_i32 s5, 0x480
	s_nop 0
	v_addc_co_u32_e32 v21, vcc, 0, v5, vcc
	v_add_co_u32_e32 v22, vcc, 0x1f8000, v4
	s_sub_i32 s1, s1, s5
	s_nop 0
	v_addc_co_u32_e32 v23, vcc, 0, v5, vcc
	global_load_dword v8, v[4:5], off
	s_nop 0
	global_load_dword v11, v[10:11], off
	s_nop 0
	global_load_dword v10, v[12:13], off
	s_nop 0
	global_load_dword v14, v[14:15], off
	s_nop 0
	global_load_dword v9, v[16:17], off
	global_load_dword v13, v[18:19], off
; __device__ __forceinline__ void tr_load_nc(const float* W, int N, int mat, int item, int lane, int nblk, float (&x)[32]) {
;     const int kb = item / nblk, nb = item % nblk, k0 = 64 * kb, n0 = 32 * nb;
;     const int sc = src_col(mat, n0 + (lane & 31));
;     const float* wp = W + (size_t)(k0 + (lane >> 5)) * N + sc;
; #pragma unroll
;     for (int i = 0; i < 32; ++i) x[i] = wp[(size_t)(2 * i) * N];
; }
; __global__ void __launch_bounds__(NTHREADS, 2) fwd(Args a) {
;     ...
;                 ldi(j + 3 * jst, x);  sti(j + jst, xn);
	global_load_dword v12, v[20:21], off
	global_load_dword v15, v[22:23], off
	v_add_co_u32_e32 v16, vcc, 0x240000, v4
	s_lshl_b32 s1, s1, 5
	s_nop 0
	v_addc_co_u32_e32 v17, vcc, 0, v5, vcc
	v_add_co_u32_e32 v18, vcc, 0x288000, v4
	s_ashr_i32 s5, s4, 31
	s_nop 0
	v_addc_co_u32_e32 v19, vcc, 0, v5, vcc
	v_add_co_u32_e32 v20, vcc, 0x2d0000, v4
	v_readlane_b32 s77, v254, 3
	s_nop 0
	v_addc_co_u32_e32 v21, vcc, 0, v5, vcc
	v_add_co_u32_e32 v22, vcc, 0x318000, v4
	v_readlane_b32 s78, v254, 4
	s_nop 0
	v_addc_co_u32_e32 v23, vcc, 0, v5, vcc
	v_add_co_u32_e32 v32, vcc, 0x360000, v4
	v_readlane_b32 s79, v254, 5
	s_nop 0
	v_addc_co_u32_e32 v33, vcc, 0, v5, vcc
	v_add_co_u32_e32 v34, vcc, 0x3a8000, v4
	v_readlane_b32 s80, v254, 6
	s_nop 0
	v_addc_co_u32_e32 v35, vcc, 0, v5, vcc
	v_add_co_u32_e32 v36, vcc, 0x3f0000, v4
	v_readlane_b32 s81, v254, 7
	s_nop 0
	v_addc_co_u32_e32 v37, vcc, 0, v5, vcc
	v_add_co_u32_e32 v38, vcc, 0x438000, v4
	v_readlane_b32 s82, v254, 8
	s_nop 0
	v_addc_co_u32_e32 v39, vcc, 0, v5, vcc
	global_load_dword v16, v[16:17], off
	s_nop 0
	global_load_dword v19, v[18:19], off
	s_nop 0
	global_load_dword v18, v[20:21], off
	s_nop 0
	global_load_dword v22, v[22:23], off
	s_nop 0
	global_load_dword v17, v[32:33], off
	global_load_dword v21, v[34:35], off
	global_load_dword v20, v[36:37], off
	global_load_dword v23, v[38:39], off
	v_add_co_u32_e32 v32, vcc, 0x480000, v4
	v_readlane_b32 s83, v254, 9
	s_nop 0
	v_addc_co_u32_e32 v33, vcc, 0, v5, vcc
	v_add_co_u32_e32 v34, vcc, 0x4c8000, v4
	v_readlane_b32 s86, v254, 12
	s_nop 0
	v_addc_co_u32_e32 v35, vcc, 0, v5, vcc
	v_add_co_u32_e32 v36, vcc, 0x510000, v4
	v_readlane_b32 s87, v254, 13
	s_nop 0
	v_addc_co_u32_e32 v37, vcc, 0, v5, vcc
	v_add_co_u32_e32 v38, vcc, 0x558000, v4
	v_readlane_b32 s88, v254, 14
	s_nop 0
	v_addc_co_u32_e32 v39, vcc, 0, v5, vcc
	v_add_co_u32_e32 v48, vcc, 0x5a0000, v4
	v_readlane_b32 s89, v254, 15
	s_nop 0
	v_addc_co_u32_e32 v49, vcc, 0, v5, vcc
	v_add_co_u32_e32 v50, vcc, 0x5e8000, v4
	v_readlane_b32 s90, v254, 16
	s_nop 0
	v_addc_co_u32_e32 v51, vcc, 0, v5, vcc
	v_add_co_u32_e32 v52, vcc, 0x630000, v4
	v_readlane_b32 s91, v254, 17
	s_nop 0
	v_addc_co_u32_e32 v53, vcc, 0, v5, vcc
	v_add_co_u32_e32 v54, vcc, 0x678000, v4
	s_nop 1
	v_addc_co_u32_e32 v55, vcc, 0, v5, vcc
	global_load_dword v32, v[32:33], off
	s_nop 0
	global_load_dword v35, v[34:35], off
	s_nop 0
	global_load_dword v34, v[36:37], off
	s_nop 0
	global_load_dword v38, v[38:39], off
	s_nop 0
	global_load_dword v33, v[48:49], off
	global_load_dword v37, v[50:51], off
	global_load_dword v36, v[52:53], off
	global_load_dword v39, v[54:55], off
	v_add_co_u32_e32 v48, vcc, 0x6c0000, v4
	s_nop 1
	v_addc_co_u32_e32 v49, vcc, 0, v5, vcc
	v_add_co_u32_e32 v50, vcc, 0x708000, v4
	s_nop 1
	v_addc_co_u32_e32 v51, vcc, 0, v5, vcc
	v_add_co_u32_e32 v52, vcc, 0x750000, v4
	s_nop 1
	v_addc_co_u32_e32 v53, vcc, 0, v5, vcc
	v_add_co_u32_e32 v54, vcc, 0x798000, v4
	s_nop 1
	v_addc_co_u32_e32 v55, vcc, 0, v5, vcc
	v_add_co_u32_e32 v118, vcc, 0x7e0000, v4
	s_nop 1
	v_addc_co_u32_e32 v119, vcc, 0, v5, vcc
	v_add_co_u32_e32 v120, vcc, 0x828000, v4
	s_nop 1
	v_addc_co_u32_e32 v121, vcc, 0, v5, vcc
	v_add_co_u32_e32 v122, vcc, 0x870000, v4
	s_nop 1
	v_addc_co_u32_e32 v123, vcc, 0, v5, vcc
	v_add_co_u32_e32 v4, vcc, 0x8b8000, v4
	s_nop 1
	v_addc_co_u32_e32 v5, vcc, 0, v5, vcc
	global_load_dword v48, v[48:49], off
	s_nop 0
	global_load_dword v51, v[50:51], off
	s_nop 0
	global_load_dword v50, v[52:53], off
	s_nop 0
	global_load_dword v54, v[54:55], off
	s_nop 0
	global_load_dword v49, v[118:119], off
	global_load_dword v53, v[120:121], off
	global_load_dword v52, v[122:123], off
	global_load_dword v55, v[4:5], off
	s_waitcnt vmcnt(63)
; #define GAS __attribute__((address_space(1)))
; #define LAS __attribute__((address_space(3)))
; #define LDS_WAIT() asm volatile("s_waitcnt lgkmcnt(0)" ::: "memory")
; __device__ __forceinline__ unsigned pk2(float lo, float hi) { return pg8::cvt_pk_bf16(lo, hi); }
; __device__ __forceinline__ void tr_store(bf16* WT, int K, LAS float* scr, int item, int lane, int nblk, const float (&x)[32]) {
;     const int kb = item / nblk, nb = item % nblk, k0 = 64 * kb, n0 = 32 * nb;
; #pragma unroll
;     for (int i = 0; i < 32; ++i) { const int kk = 2 * i + (lane >> 5); scr[kk * 33 + (lane & 31)] = x[i]; }
;     LDS_WAIT(); asm volatile("" ::: "memory");
;     const int c = lane & 7;
; #pragma unroll
;     for (int j = 0; j < 4; ++j) { const int n = (lane >> 3) + 8 * j; const LAS float* s = scr + (8 * c) * 33 + n;
;         v4u o; o.x = pk2(s[0 * 33], s[1 * 33]); o.y = pk2(s[2 * 33], s[3 * 33]); o.z = pk2(s[4 * 33], s[5 * 33]); o.w = pk2(s[6 * 33], s[7 * 33]);
;         *(GAS v4u*)(WT + (size_t)(n0 + n) * K + k0 + 8 * c) = o; }
;     LDS_WAIT(); asm volatile("" ::: "memory");
; __global__ void __launch_bounds__(NTHREADS, 2) fwd(Args a) {
;     ...
;                 ldi(j + 4 * jst, xn); sti(j + 2 * jst, xc);
	ds_write2_b32 v65, v24, v26 offset1:66
	ds_write2_b32 v65, v25, v28 offset0:132 offset1:198
	ds_write2_b32 v111, v27, v30 offset0:8 offset1:74
	ds_write2_b32 v111, v29, v31 offset0:140 offset1:206
	ds_write2_b32 v112, v40, v42 offset0:16 offset1:82
	ds_write2_b32 v112, v41, v44 offset0:148 offset1:214
	ds_write2_b32 v113, v43, v46 offset0:24 offset1:90
	ds_write2_b32 v113, v45, v47 offset0:156 offset1:222
	ds_write2_b32 v114, v56, v58 offset0:32 offset1:98
	ds_write2_b32 v114, v57, v60 offset0:164 offset1:230
	ds_write2_b32 v115, v59, v62 offset0:40 offset1:106
	ds_write2_b32 v115, v61, v63 offset0:172 offset1:238
	ds_write2_b32 v116, v64, v67 offset0:48 offset1:114
	ds_write2_b32 v116, v66, v70 offset0:180 offset1:246
	ds_write2_b32 v117, v69, v72 offset0:56 offset1:122
	ds_write2_b32 v117, v71, v73 offset0:188 offset1:254
	s_waitcnt lgkmcnt(0)
	ds_read2_b32 v[4:5], v74 offset1:33
	s_waitcnt lgkmcnt(0)
	v_cvt_pk_bf16_f32 v24, v4, v5
	ds_read2_b32 v[4:5], v74 offset0:66 offset1:99
	s_waitcnt lgkmcnt(0)
	v_cvt_pk_bf16_f32 v25, v4, v5
	ds_read2_b32 v[4:5], v74 offset0:132 offset1:165
	s_waitcnt lgkmcnt(0)
	v_cvt_pk_bf16_f32 v26, v4, v5
	ds_read2_b32 v[4:5], v74 offset0:198 offset1:231
	s_waitcnt lgkmcnt(0)
	v_cvt_pk_bf16_f32 v27, v4, v5
	v_or_b32_e32 v4, s1, v68
	v_ashrrev_i32_e32 v5, 31, v4
	v_lshl_add_u64 v[28:29], s[4:5], 1, v[2:3]
	v_lshlrev_b64 v[4:5], 13, v[4:5]
	v_lshl_add_u64 v[4:5], v[28:29], 0, v[4:5]
	ds_read2_b32 v[30:31], v74 offset0:8 offset1:41
	global_store_dwordx4 v[4:5], v[24:27], off
	s_waitcnt lgkmcnt(0)
	s_nop 0
	v_cvt_pk_bf16_f32 v24, v30, v31
	ds_read2_b32 v[4:5], v74 offset0:74 offset1:107
	s_waitcnt lgkmcnt(0)
	v_cvt_pk_bf16_f32 v25, v4, v5
	ds_read2_b32 v[4:5], v74 offset0:140 offset1:173
	s_waitcnt lgkmcnt(0)
	v_cvt_pk_bf16_f32 v26, v4, v5
	ds_read2_b32 v[4:5], v74 offset0:206 offset1:239
	s_waitcnt lgkmcnt(0)
	v_cvt_pk_bf16_f32 v27, v4, v5
	v_or_b32_e32 v4, s1, v75
	v_ashrrev_i32_e32 v5, 31, v4
	v_lshlrev_b64 v[4:5], 13, v[4:5]
	v_lshl_add_u64 v[4:5], v[28:29], 0, v[4:5]
	ds_read2_b32 v[30:31], v74 offset0:16 offset1:49
	global_store_dwordx4 v[4:5], v[24:27], off
	s_waitcnt lgkmcnt(0)
	s_nop 0
	v_cvt_pk_bf16_f32 v24, v30, v31
	ds_read2_b32 v[4:5], v74 offset0:82 offset1:115
	s_waitcnt lgkmcnt(0)
	v_cvt_pk_bf16_f32 v25, v4, v5
	ds_read2_b32 v[4:5], v74 offset0:148 offset1:181
	s_waitcnt lgkmcnt(0)
	v_cvt_pk_bf16_f32 v26, v4, v5
	ds_read2_b32 v[4:5], v74 offset0:214 offset1:247
	s_waitcnt lgkmcnt(0)
	v_cvt_pk_bf16_f32 v27, v4, v5
	v_or_b32_e32 v4, s1, v76
	v_ashrrev_i32_e32 v5, 31, v4
	v_lshlrev_b64 v[4:5], 13, v[4:5]
	v_lshl_add_u64 v[4:5], v[28:29], 0, v[4:5]
	ds_read2_b32 v[30:31], v74 offset0:24 offset1:57
	global_store_dwordx4 v[4:5], v[24:27], off
	s_waitcnt lgkmcnt(0)
	s_nop 0
	v_cvt_pk_bf16_f32 v24, v30, v31
	ds_read2_b32 v[4:5], v74 offset0:90 offset1:123
	s_waitcnt lgkmcnt(0)
	v_cvt_pk_bf16_f32 v25, v4, v5
	ds_read2_b32 v[4:5], v74 offset0:156 offset1:189
	s_waitcnt lgkmcnt(0)
	v_cvt_pk_bf16_f32 v26, v4, v5
	ds_read2_b32 v[4:5], v74 offset0:222 offset1:255
	s_waitcnt lgkmcnt(0)
	v_cvt_pk_bf16_f32 v27, v4, v5
	v_or_b32_e32 v4, s1, v77
	s_add_i32 s1, s16, s20
	s_min_i32 s4, s1, s100
	v_ashrrev_i32_e32 v5, 31, v4
	s_mul_hi_i32 s1, s4, 0x38e38e39
	v_lshlrev_b64 v[4:5], 13, v[4:5]
	s_lshr_b32 s5, s1, 31
	s_ashr_i32 s1, s1, 8
	v_lshl_add_u64 v[4:5], v[28:29], 0, v[4:5]
	s_add_i32 s1, s1, s5
	global_store_dwordx4 v[4:5], v[24:27], off
	s_mul_i32 s5, s1, 0x480
	s_waitcnt lgkmcnt(0)
	s_sub_i32 s4, s4, s5
	s_lshl_b32 s6, s4, 5
	v_or_b32_e32 v5, s6, v6
	v_cmp_lt_i32_e32 vcc, s17, v5
	s_and_saveexec_b64 s[4:5], vcc
	s_xor_b64 s[4:5], exec, s[4:5]
	s_cbranch_execz .LBB0_705
	s_add_i32 s20, s6, 0xffffd000
	s_lshr_b32 s20, s20, 1
	v_cmp_gt_u32_sdwa s[6:7], v5, s18 src0_sel:BYTE_0 src1_sel:DWORD
	s_and_b32 s20, s20, 0x7fffff80
	s_and_saveexec_b64 s[22:23], s[6:7]
	s_xor_b64 s[6:7], exec, s[22:23]
	v_add_u32_sdwa v4, v5, s20 dst_sel:DWORD dst_unused:UNUSED_PAD src0_sel:BYTE_0 src1_sel:DWORD
	v_add_u32_e32 v4, 0x5f80, v4
	s_andn2_saveexec_b64 s[6:7], s[6:7]
	v_or_b32_sdwa v4, s20, v5 dst_sel:DWORD dst_unused:UNUSED_PAD src0_sel:DWORD src1_sel:BYTE_0
	s_or_b64 exec, exec, s[6:7]

; #define GAS __attribute__((address_space(1)))
; #define LAS __attribute__((address_space(3)))
; #define LDS_WAIT() asm volatile("s_waitcnt lgkmcnt(0)" ::: "memory")
; __device__ __forceinline__ unsigned pk2(float lo, float hi) { return pg8::cvt_pk_bf16(lo, hi); }
; __device__ __forceinline__ void tr_store(bf16* WT, int K, LAS float* scr, int item, int lane, int nblk, const float (&x)[32]) {
;     const int kb = item / nblk, nb = item % nblk, k0 = 64 * kb, n0 = 32 * nb;
; #pragma unroll
;     for (int i = 0; i < 32; ++i) { const int kk = 2 * i + (lane >> 5); scr[kk * 33 + (lane & 31)] = x[i]; }
;     LDS_WAIT(); asm volatile("" ::: "memory");
;     const int c = lane & 7;
; #pragma unroll
;     for (int j = 0; j < 4; ++j) { const int n = (lane >> 3) + 8 * j; const LAS float* s = scr + (8 * c) * 33 + n;
;         v4u o; o.x = pk2(s[0 * 33], s[1 * 33]); o.y = pk2(s[2 * 33], s[3 * 33]); o.z = pk2(s[4 * 33], s[5 * 33]); o.w = pk2(s[6 * 33], s[7 * 33]);
;         *(GAS v4u*)(WT + (size_t)(n0 + n) * K + k0 + 8 * c) = o; }
;     LDS_WAIT(); asm volatile("" ::: "memory");
; __global__ void __launch_bounds__(NTHREADS, 2) fwd(Args a) {
;     ...
;             if (j < L1_P5) sti(j, x);
.LBB0_707:
	s_cmp_gt_i32 s10, s100
	s_cbranch_scc1 .LBB0_709
	v_lshlrev_b32_e32 v2, 2, v6
	v_mul_u32_u24_e32 v3, 0x84, v7
	v_add3_u32 v2, s9, v2, v3
	v_add_u32_e32 v3, 0x400, v2
	s_waitcnt vmcnt(0)
	ds_write2_b32 v2, v8, v11 offset1:66
	ds_write2_b32 v2, v10, v14 offset0:132 offset1:198
	ds_write2_b32 v3, v9, v13 offset0:8 offset1:74
	ds_write2_b32 v3, v12, v15 offset0:140 offset1:206
	v_add_u32_e32 v3, 0x800, v2
	ds_write2_b32 v3, v16, v19 offset0:16 offset1:82
	ds_write2_b32 v3, v18, v22 offset0:148 offset1:214
	v_add_u32_e32 v3, 0xc00, v2
	ds_write2_b32 v3, v17, v21 offset0:24 offset1:90
	ds_write2_b32 v3, v20, v23 offset0:156 offset1:222
	v_add_u32_e32 v3, 0x1000, v2
	ds_write2_b32 v3, v32, v35 offset0:32 offset1:98
	ds_write2_b32 v3, v34, v38 offset0:164 offset1:230
	v_add_u32_e32 v3, 0x1400, v2
	ds_write2_b32 v3, v33, v37 offset0:40 offset1:106
	ds_write2_b32 v3, v36, v39 offset0:172 offset1:238
	v_add_u32_e32 v3, 0x1800, v2
	v_add_u32_e32 v2, 0x1c00, v2
	ds_write2_b32 v3, v48, v51 offset0:48 offset1:114
	ds_write2_b32 v3, v50, v54 offset0:180 offset1:246
	ds_write2_b32 v2, v49, v53 offset0:56 offset1:122
	ds_write2_b32 v2, v52, v55 offset0:188 offset1:254
	v_lshlrev_b32_e32 v2, 3, v1
	v_lshrrev_b32_e32 v12, 3, v1
	v_and_b32_e32 v10, 56, v2
	s_waitcnt lgkmcnt(0)
	v_mul_u32_u24_e32 v2, 0x84, v10
	v_lshlrev_b32_e32 v3, 2, v12
	s_mul_hi_i32 s0, s10, 0x38e38e39
	v_add3_u32 v16, s9, v2, v3
	s_lshr_b32 s1, s0, 31
	s_ashr_i32 s0, s0, 8
	ds_read2_b32 v[2:3], v16 offset1:33
	s_add_i32 s1, s0, s1
	s_waitcnt lgkmcnt(0)
	v_cvt_pk_bf16_f32 v2, v2, v3
	ds_read2_b32 v[4:5], v16 offset0:66 offset1:99
	s_lshl_b32 s0, s1, 6
	s_mulk_i32 s1, 0x480
	s_waitcnt lgkmcnt(0)
	v_cvt_pk_bf16_f32 v3, v4, v5
	ds_read2_b32 v[4:5], v16 offset0:132 offset1:165
	s_sub_i32 s4, s10, s1
	s_ashr_i32 s1, s0, 31
	s_lshl_b64 s[0:1], s[0:1], 1
	s_waitcnt lgkmcnt(0)
	v_cvt_pk_bf16_f32 v4, v4, v5
	ds_read2_b32 v[8:9], v16 offset0:198 offset1:231
	s_add_u32 s0, s92, s0
	s_waitcnt lgkmcnt(0)
	v_cvt_pk_bf16_f32 v5, v8, v9
	v_lshl_or_b32 v8, s4, 5, v12
	s_addc_u32 s1, s93, s1
	v_lshlrev_b32_e32 v10, 1, v10
	v_mov_b32_e32 v11, 0
	v_ashrrev_i32_e32 v9, 31, v8
	v_lshl_add_u64 v[10:11], s[0:1], 0, v[10:11]
	v_lshlrev_b64 v[14:15], 13, v[8:9]
	v_lshl_add_u64 v[14:15], v[10:11], 0, v[14:15]
	ds_read2_b32 v[12:13], v16 offset0:8 offset1:41
	global_store_dwordx4 v[14:15], v[2:5], off
	s_waitcnt lgkmcnt(0)
	s_nop 0
	v_cvt_pk_bf16_f32 v2, v12, v13
	ds_read2_b32 v[4:5], v16 offset0:74 offset1:107
	s_waitcnt lgkmcnt(0)
	v_cvt_pk_bf16_f32 v3, v4, v5
	ds_read2_b32 v[4:5], v16 offset0:140 offset1:173
	s_waitcnt lgkmcnt(0)
	v_cvt_pk_bf16_f32 v4, v4, v5
	ds_read2_b32 v[12:13], v16 offset0:206 offset1:239
	s_waitcnt lgkmcnt(0)
	v_cvt_pk_bf16_f32 v5, v12, v13
	v_or_b32_e32 v12, 8, v8
	v_ashrrev_i32_e32 v13, 31, v12
	v_lshlrev_b64 v[12:13], 13, v[12:13]
	v_lshl_add_u64 v[12:13], v[10:11], 0, v[12:13]
	ds_read2_b32 v[14:15], v16 offset0:16 offset1:49
	global_store_dwordx4 v[12:13], v[2:5], off
	s_waitcnt lgkmcnt(0)
	s_nop 0
	v_cvt_pk_bf16_f32 v2, v14, v15
	ds_read2_b32 v[4:5], v16 offset0:82 offset1:115
	s_waitcnt lgkmcnt(0)
	v_cvt_pk_bf16_f32 v3, v4, v5
	ds_read2_b32 v[4:5], v16 offset0:148 offset1:181
	s_waitcnt lgkmcnt(0)
	v_cvt_pk_bf16_f32 v4, v4, v5
	ds_read2_b32 v[12:13], v16 offset0:214 offset1:247
	s_waitcnt lgkmcnt(0)
	v_cvt_pk_bf16_f32 v5, v12, v13
	v_or_b32_e32 v12, 16, v8
	v_ashrrev_i32_e32 v13, 31, v12
	v_lshlrev_b64 v[12:13], 13, v[12:13]
	v_or_b32_e32 v8, 24, v8
	v_lshl_add_u64 v[12:13], v[10:11], 0, v[12:13]
	v_ashrrev_i32_e32 v9, 31, v8
	ds_read2_b32 v[14:15], v16 offset0:24 offset1:57
	global_store_dwordx4 v[12:13], v[2:5], off
	v_lshlrev_b64 v[8:9], 13, v[8:9]
	v_lshl_add_u64 v[8:9], v[10:11], 0, v[8:9]
	s_waitcnt lgkmcnt(0)
	v_cvt_pk_bf16_f32 v2, v14, v15
	ds_read2_b32 v[4:5], v16 offset0:90 offset1:123
	s_waitcnt lgkmcnt(0)
	v_cvt_pk_bf16_f32 v3, v4, v5
	ds_read2_b32 v[4:5], v16 offset0:156 offset1:189
	s_waitcnt lgkmcnt(0)
	v_cvt_pk_bf16_f32 v4, v4, v5
	ds_read2_b32 v[12:13], v16 offset0:222 offset1:255
	s_waitcnt lgkmcnt(0)
	v_cvt_pk_bf16_f32 v5, v12, v13
	global_store_dwordx4 v[8:9], v[2:5], off
	s_waitcnt lgkmcnt(0)
; #define GAS __attribute__((address_space(1)))
; #define LAS __attribute__((address_space(3)))
; #define LDS_WAIT() asm volatile("s_waitcnt lgkmcnt(0)" ::: "memory")
; __device__ __forceinline__ unsigned pk2(float lo, float hi) { return pg8::cvt_pk_bf16(lo, hi); }
; __device__ __forceinline__ void tr_store(bf16* WT, int K, LAS float* scr, int item, int lane, int nblk, const float (&x)[32]) {
;     const int kb = item / nblk, nb = item % nblk, k0 = 64 * kb, n0 = 32 * nb;
; #pragma unroll
;     for (int i = 0; i < 32; ++i) { const int kk = 2 * i + (lane >> 5); scr[kk * 33 + (lane & 31)] = x[i]; }
;     LDS_WAIT(); asm volatile("" ::: "memory");
;     const int c = lane & 7;
; #pragma unroll
;     for (int j = 0; j < 4; ++j) { const int n = (lane >> 3) + 8 * j; const LAS float* s = scr + (8 * c) * 33 + n;
;         v4u o; o.x = pk2(s[0 * 33], s[1 * 33]); o.y = pk2(s[2 * 33], s[3 * 33]); o.z = pk2(s[4 * 33], s[5 * 33]); o.w = pk2(s[6 * 33], s[7 * 33]);
;         *(GAS v4u*)(WT + (size_t)(n0 + n) * K + k0 + 8 * c) = o; }
;     LDS_WAIT(); asm volatile("" ::: "memory");
; __global__ void __launch_bounds__(NTHREADS, 2) fwd(Args a) {
;     ...
;             if (j + jst < L1_P5) sti(j + jst, xn);
.LBB0_709:
	s_add_i32 s0, s10, s8
	s_cmp_gt_i32 s0, s100
	s_cbranch_scc1 .LBB0_711
	v_lshlrev_b32_e32 v2, 2, v6
	v_mul_u32_u24_e32 v3, 0x84, v7
	v_add3_u32 v2, s9, v2, v3
	v_add_u32_e32 v3, 0x400, v2
	s_waitcnt vmcnt(0)
	ds_write2_b32 v2, v24, v26 offset1:66
	ds_write2_b32 v2, v25, v28 offset0:132 offset1:198
	ds_write2_b32 v3, v27, v30 offset0:8 offset1:74
	ds_write2_b32 v3, v29, v31 offset0:140 offset1:206
	v_add_u32_e32 v3, 0x800, v2
	ds_write2_b32 v3, v40, v42 offset0:16 offset1:82
	ds_write2_b32 v3, v41, v44 offset0:148 offset1:214
	v_add_u32_e32 v3, 0xc00, v2
	ds_write2_b32 v3, v43, v46 offset0:24 offset1:90
	ds_write2_b32 v3, v45, v47 offset0:156 offset1:222
	v_add_u32_e32 v3, 0x1000, v2
	ds_write2_b32 v3, v56, v58 offset0:32 offset1:98
	ds_write2_b32 v3, v57, v60 offset0:164 offset1:230
	v_add_u32_e32 v3, 0x1400, v2
	ds_write2_b32 v3, v59, v62 offset0:40 offset1:106
	ds_write2_b32 v3, v61, v63 offset0:172 offset1:238
	v_add_u32_e32 v3, 0x1800, v2
	v_add_u32_e32 v2, 0x1c00, v2
	v_lshrrev_b32_e32 v10, 3, v1
	v_lshlrev_b32_e32 v1, 3, v1
	ds_write2_b32 v3, v64, v67 offset0:48 offset1:114
	ds_write2_b32 v3, v66, v70 offset0:180 offset1:246
	ds_write2_b32 v2, v69, v72 offset0:56 offset1:122
	ds_write2_b32 v2, v71, v73 offset0:188 offset1:254
	v_and_b32_e32 v1, 56, v1
	s_waitcnt lgkmcnt(0)
	v_mul_u32_u24_e32 v2, 0x84, v1
	v_lshlrev_b32_e32 v3, 2, v10
	s_mul_hi_i32 s1, s0, 0x38e38e39
	v_add3_u32 v14, s9, v2, v3
	s_lshr_b32 s4, s1, 31
	s_ashr_i32 s1, s1, 8
	ds_read2_b32 v[2:3], v14 offset1:33
	s_add_i32 s1, s1, s4
	s_waitcnt lgkmcnt(0)
	v_cvt_pk_bf16_f32 v2, v2, v3
	ds_read2_b32 v[4:5], v14 offset0:66 offset1:99
	s_lshl_b32 s4, s1, 6
	s_mulk_i32 s1, 0x480
	s_waitcnt lgkmcnt(0)
	v_cvt_pk_bf16_f32 v3, v4, v5
	ds_read2_b32 v[4:5], v14 offset0:132 offset1:165
	s_ashr_i32 s5, s4, 31
	s_sub_i32 s6, s0, s1
	s_lshl_b64 s[0:1], s[4:5], 1
	s_waitcnt lgkmcnt(0)
	v_cvt_pk_bf16_f32 v4, v4, v5
	ds_read2_b32 v[6:7], v14 offset0:198 offset1:231
	s_add_u32 s0, s92, s0
	s_waitcnt lgkmcnt(0)
	v_cvt_pk_bf16_f32 v5, v6, v7
	v_lshl_or_b32 v6, s6, 5, v10
	s_addc_u32 s1, s93, s1
	v_lshlrev_b32_e32 v8, 1, v1
	v_mov_b32_e32 v9, 0
	v_ashrrev_i32_e32 v7, 31, v6
	v_lshl_add_u64 v[8:9], s[0:1], 0, v[8:9]
	v_lshlrev_b64 v[12:13], 13, v[6:7]
	v_lshl_add_u64 v[12:13], v[8:9], 0, v[12:13]
	ds_read2_b32 v[10:11], v14 offset0:8 offset1:41
	global_store_dwordx4 v[12:13], v[2:5], off
	s_waitcnt lgkmcnt(0)
	s_nop 0
	v_cvt_pk_bf16_f32 v2, v10, v11
	ds_read2_b32 v[4:5], v14 offset0:74 offset1:107
	s_waitcnt lgkmcnt(0)
	v_cvt_pk_bf16_f32 v3, v4, v5
	ds_read2_b32 v[4:5], v14 offset0:140 offset1:173
	s_waitcnt lgkmcnt(0)
	v_cvt_pk_bf16_f32 v4, v4, v5
	ds_read2_b32 v[10:11], v14 offset0:206 offset1:239
	s_waitcnt lgkmcnt(0)
	v_cvt_pk_bf16_f32 v5, v10, v11
	v_or_b32_e32 v10, 8, v6
	v_ashrrev_i32_e32 v11, 31, v10
	v_lshlrev_b64 v[10:11], 13, v[10:11]
	v_lshl_add_u64 v[10:11], v[8:9], 0, v[10:11]
	ds_read2_b32 v[12:13], v14 offset0:16 offset1:49
	global_store_dwordx4 v[10:11], v[2:5], off
	s_waitcnt lgkmcnt(0)
	s_nop 0
	v_cvt_pk_bf16_f32 v2, v12, v13
	ds_read2_b32 v[4:5], v14 offset0:82 offset1:115
	s_waitcnt lgkmcnt(0)
	v_cvt_pk_bf16_f32 v3, v4, v5
	ds_read2_b32 v[4:5], v14 offset0:148 offset1:181
	s_waitcnt lgkmcnt(0)
	v_cvt_pk_bf16_f32 v4, v4, v5
	ds_read2_b32 v[10:11], v14 offset0:214 offset1:247
	s_waitcnt lgkmcnt(0)
	v_cvt_pk_bf16_f32 v5, v10, v11
	v_or_b32_e32 v10, 16, v6
	v_ashrrev_i32_e32 v11, 31, v10
	v_lshlrev_b64 v[10:11], 13, v[10:11]
	v_or_b32_e32 v6, 24, v6
	v_lshl_add_u64 v[10:11], v[8:9], 0, v[10:11]
	v_ashrrev_i32_e32 v7, 31, v6
	ds_read2_b32 v[12:13], v14 offset0:24 offset1:57
	global_store_dwordx4 v[10:11], v[2:5], off
	v_lshlrev_b64 v[6:7], 13, v[6:7]
	v_lshl_add_u64 v[6:7], v[8:9], 0, v[6:7]
	s_waitcnt lgkmcnt(0)
	v_cvt_pk_bf16_f32 v2, v12, v13
	ds_read2_b32 v[4:5], v14 offset0:90 offset1:123
	s_waitcnt lgkmcnt(0)
	v_cvt_pk_bf16_f32 v3, v4, v5
	ds_read2_b32 v[4:5], v14 offset0:156 offset1:189
	s_waitcnt lgkmcnt(0)
	v_cvt_pk_bf16_f32 v4, v4, v5
	ds_read2_b32 v[10:11], v14 offset0:222 offset1:255
	s_waitcnt lgkmcnt(0)
	v_cvt_pk_bf16_f32 v5, v10, v11
	global_store_dwordx4 v[6:7], v[2:5], off
	s_waitcnt lgkmcnt(0)
